# chain workgroups go straight to the eight-queue sweep after their chain (one round trip instead of poll own queue + sweep)
# speedup vs baseline: 1.0004x; 1.0004x over previous
.LBB0_1096:
	s_or_b64 exec, exec, s[6:7]
	v_pk_mul_f32 v[2:3], v[20:21], v[10:11]
	s_waitcnt vmcnt(2)
	v_lshlrev_b32_e32 v10, 16, v36
	v_and_b32_e32 v11, 0xffff0000, v36
	v_mul_f32_e32 v12, 0xbfb8aa3b, v10
	v_mul_f32_e32 v13, 0xbfb8aa3b, v11
	v_exp_f32_e32 v12, v12
	v_exp_f32_e32 v13, v13
	v_add_co_u32_e32 v0, vcc, 0x12840000, v0
	v_add_f32_e32 v12, 1.0, v12
	v_add_f32_e32 v13, 1.0, v13
	v_rcp_f32_e32 v12, v12
	v_rcp_f32_e32 v13, v13
	v_addc_co_u32_e32 v1, vcc, 0, v1, vcc
	v_pk_mul_f32 v[10:11], v[12:13], v[10:11]
	s_nop 0
	v_pk_mul_f32 v[2:3], v[10:11], v[2:3]
	s_nop 0
	v_cvt_pk_bf16_f32 v10, v2, v3
	v_pk_mul_f32 v[2:3], v[22:23], v[8:9]
	v_lshlrev_b32_e32 v8, 16, v37
	v_mul_f32_e32 v11, 0xbfb8aa3b, v8
	v_exp_f32_e32 v11, v11
	v_and_b32_e32 v9, 0xffff0000, v37
	v_add_f32_e32 v11, 1.0, v11
	v_rcp_f32_e32 v12, v11
	v_mul_f32_e32 v11, 0xbfb8aa3b, v9
	v_exp_f32_e32 v11, v11
	s_nop 0
	v_add_f32_e32 v11, 1.0, v11
	v_rcp_f32_e32 v13, v11
	s_nop 0
	v_pk_mul_f32 v[8:9], v[12:13], v[8:9]
	s_nop 0
	v_pk_mul_f32 v[2:3], v[8:9], v[2:3]
	s_nop 0
	v_cvt_pk_bf16_f32 v11, v2, v3
	v_pk_mul_f32 v[2:3], v[16:17], v[6:7]
	v_lshlrev_b32_e32 v6, 16, v38
	v_and_b32_e32 v7, 0xffff0000, v38
	v_mul_f32_e32 v8, 0xbfb8aa3b, v6
	v_mul_f32_e32 v9, 0xbfb8aa3b, v7
	v_exp_f32_e32 v8, v8
	v_exp_f32_e32 v9, v9
	v_add_f32_e32 v8, 1.0, v8
	v_add_f32_e32 v9, 1.0, v9
	v_rcp_f32_e32 v8, v8
	v_rcp_f32_e32 v9, v9
	s_nop 0
	v_pk_mul_f32 v[6:7], v[8:9], v[6:7]
	s_nop 0
	v_pk_mul_f32 v[2:3], v[6:7], v[2:3]
	s_nop 0
	v_cvt_pk_bf16_f32 v12, v2, v3
	v_pk_mul_f32 v[2:3], v[18:19], v[4:5]
	v_lshlrev_b32_e32 v4, 16, v39
	v_and_b32_e32 v5, 0xffff0000, v39
	v_mul_f32_e32 v6, 0xbfb8aa3b, v4
	v_mul_f32_e32 v7, 0xbfb8aa3b, v5
	v_exp_f32_e32 v6, v6
	v_exp_f32_e32 v7, v7
	v_add_f32_e32 v6, 1.0, v6
	v_add_f32_e32 v7, 1.0, v7
	v_rcp_f32_e32 v6, v6
	v_rcp_f32_e32 v7, v7
	s_nop 0
	v_pk_mul_f32 v[4:5], v[6:7], v[4:5]
	s_nop 0
	v_pk_mul_f32 v[2:3], v[4:5], v[2:3]
	s_nop 0
	v_cvt_pk_bf16_f32 v13, v2, v3
	global_store_dwordx4 v[0:1], v[10:13], off
	s_waitcnt lgkmcnt(0)
	s_barrier
	s_barrier
	s_mov_b32 s31, -1
	s_branch .LBB0_1098
